# combo+gblk+poolh + blocked 1KB-contiguous layout for the PLE bf16 buffer (producer EpiPlain, consumer EpiGate)
# baseline (speedup 1.0000x reference)
; __device__ __forceinline__ u32x4 pack8(f32x4 a, f32x4 b) { u32x4 w; w.x = cvt_pk_bf16(a[0], a[1]); w.y = cvt_pk_bf16(a[2], a[3]); w.z = cvt_pk_bf16(b[0], b[1]); w.w = cvt_pk_bf16(b[2], b[3]); return w; }
; #define EPI_OPAQUE asm volatile("" : "+v"(fr), "+v"(fq));
;     __device__ __forceinline__ void operator()(f32x4 (&acc)[2][2][4][2], const Unit& u, int wr, int wc, int fr, int fq) const {
;         EPI_OPAQUE
;         EPI_ROWS_BEGIN EPI_COLS_BEGIN
;             *(u32x4*)(O + (size_t)row * ldo + col) = pack8(acc[ai][bj][m][0], acc[ai][bj][m][1]);
;         EPI_END EPI_END
;     }
.LBB0_524:
	s_lshl_b32 s4, s56, 8
	v_mov_b32_e32 v141, v1
	v_mov_b32_e32 v143, v138
	s_add_i32 s4, s4, s24
	v_cvt_pk_bf16_f32 v70, v70, v71
	v_add_u32_e32 v142, s4, v141
	s_lshl_b32 s4, s46, 8
	s_or_b32 s4, s4, s25
	v_cvt_pk_bf16_f32 v71, v72, v73
	v_cvt_pk_bf16_f32 v72, v66, v67
	v_add_u32_e32 v66, 0x80, v142
	v_lshl_add_u32 v144, v143, 3, s4
	v_ashrrev_i32_e32 v143, 31, v142
	v_ashrrev_i32_e32 v67, 31, v66
	v_cvt_pk_bf16_f32 v126, v126, v127
	v_cvt_pk_bf16_f32 v127, v128, v129
	v_cvt_pk_bf16_f32 v128, v122, v123
	v_lshlrev_b64 v[122:123], 12, v[142:143]
	v_ashrrev_i32_e32 v145, 31, v144
	v_cvt_pk_bf16_f32 v62, v62, v63
	v_cvt_pk_bf16_f32 v63, v64, v65
	v_cvt_pk_bf16_f32 v64, v58, v59
	v_lshlrev_b64 v[58:59], 12, v[66:67]
	v_cvt_pk_bf16_f32 v129, v124, v125
	v_lshl_add_u64 v[122:123], s[44:45], 0, v[122:123]
	s_lshl_b32 s98, s46, 13
	s_lshl_b32 s99, s25, 6
	s_add_i32 s98, s98, s99
	s_movk_i32 s99, 0xf010
	v_lshl_add_u32 v124, v138, 8, s98
	v_mad_i32_i24 v124, v1, s99, v124
	v_ashrrev_i32_e32 v125, 31, v124
	v_lshl_add_u64 v[58:59], s[44:45], 0, v[58:59]
	v_lshl_add_u64 v[122:123], v[122:123], 0, v[124:125]
	v_cvt_pk_bf16_f32 v110, v110, v111
	v_cvt_pk_bf16_f32 v111, v112, v113
	v_cvt_pk_bf16_f32 v112, v106, v107
	v_cvt_pk_bf16_f32 v113, v108, v109
	v_lshl_add_u64 v[58:59], v[58:59], 0, v[124:125]
	v_cvt_pk_bf16_f32 v46, v46, v47
	v_cvt_pk_bf16_f32 v47, v48, v49
	v_cvt_pk_bf16_f32 v48, v42, v43
	v_cvt_pk_bf16_f32 v49, v44, v45
	global_store_dwordx4 v[122:123], v[110:113], off offset:1024
	global_store_dwordx4 v[58:59], v[46:49], off offset:1024
	v_cvt_pk_bf16_f32 v94, v94, v95
	v_add_u32_e32 v110, 16, v142
	v_add_u32_e32 v46, 0x90, v142
	v_ashrrev_i32_e32 v111, 31, v110
	v_ashrrev_i32_e32 v47, 31, v46
	v_lshlrev_b64 v[110:111], 12, v[110:111]
	v_lshlrev_b64 v[46:47], 12, v[46:47]
	v_lshl_add_u64 v[110:111], s[44:45], 0, v[110:111]
	v_lshl_add_u64 v[46:47], s[44:45], 0, v[46:47]
	v_lshl_add_u64 v[110:111], v[110:111], 0, v[124:125]
	v_cvt_pk_bf16_f32 v95, v96, v97
	v_cvt_pk_bf16_f32 v96, v90, v91
	v_cvt_pk_bf16_f32 v97, v92, v93
	v_lshl_add_u64 v[46:47], v[46:47], 0, v[124:125]
	v_cvt_pk_bf16_f32 v30, v30, v31
	v_cvt_pk_bf16_f32 v31, v32, v33
	v_cvt_pk_bf16_f32 v32, v26, v27
	v_cvt_pk_bf16_f32 v33, v28, v29
	global_store_dwordx4 v[110:111], v[94:97], off offset:1024
	global_store_dwordx4 v[46:47], v[30:33], off offset:1024
	v_cvt_pk_bf16_f32 v78, v78, v79
	v_add_u32_e32 v94, 32, v142
	v_add_u32_e32 v30, 0xa0, v142
	v_ashrrev_i32_e32 v95, 31, v94
	v_ashrrev_i32_e32 v31, 31, v30
	v_lshlrev_b64 v[94:95], 12, v[94:95]
	v_lshlrev_b64 v[30:31], 12, v[30:31]
	v_lshl_add_u64 v[94:95], s[44:45], 0, v[94:95]
	v_lshl_add_u64 v[30:31], s[44:45], 0, v[30:31]
	v_lshl_add_u64 v[94:95], v[94:95], 0, v[124:125]
	v_cvt_pk_bf16_f32 v79, v80, v81
	v_cvt_pk_bf16_f32 v80, v74, v75
	v_cvt_pk_bf16_f32 v81, v76, v77
	v_lshl_add_u64 v[30:31], v[30:31], 0, v[124:125]
	v_cvt_pk_bf16_f32 v14, v14, v15
	v_cvt_pk_bf16_f32 v15, v16, v17
	v_cvt_pk_bf16_f32 v16, v10, v11
	v_cvt_pk_bf16_f32 v17, v12, v13
	global_store_dwordx4 v[94:95], v[78:81], off offset:1024
	global_store_dwordx4 v[30:31], v[14:17], off offset:1024
	v_cvt_pk_bf16_f32 v106, v118, v119
	v_add_u32_e32 v78, 48, v142
	v_add_u32_e32 v14, 0xb0, v142
	v_ashrrev_i32_e32 v79, 31, v78
	v_ashrrev_i32_e32 v15, 31, v14
	v_lshlrev_b64 v[78:79], 12, v[78:79]
	v_lshlrev_b64 v[14:15], 12, v[14:15]
	v_lshl_add_u64 v[78:79], s[44:45], 0, v[78:79]
	v_lshl_add_u64 v[14:15], s[44:45], 0, v[14:15]
	v_cvt_pk_bf16_f32 v107, v120, v121
	v_cvt_pk_bf16_f32 v108, v114, v115
	v_cvt_pk_bf16_f32 v109, v116, v117
	v_cvt_pk_bf16_f32 v90, v102, v103
	v_cvt_pk_bf16_f32 v91, v104, v105
	v_cvt_pk_bf16_f32 v92, v98, v99
	v_cvt_pk_bf16_f32 v93, v100, v101
	v_cvt_pk_bf16_f32 v74, v86, v87
	v_cvt_pk_bf16_f32 v75, v88, v89
	v_cvt_pk_bf16_f32 v76, v82, v83
	v_cvt_pk_bf16_f32 v77, v84, v85
	v_lshl_add_u64 v[78:79], v[78:79], 0, v[124:125]
	v_cvt_pk_bf16_f32 v73, v68, v69
	v_cvt_pk_bf16_f32 v65, v60, v61
	v_cvt_pk_bf16_f32 v42, v54, v55
	v_cvt_pk_bf16_f32 v43, v56, v57
	v_cvt_pk_bf16_f32 v44, v50, v51
	v_cvt_pk_bf16_f32 v45, v52, v53
	v_cvt_pk_bf16_f32 v26, v38, v39
	v_cvt_pk_bf16_f32 v27, v40, v41
	v_cvt_pk_bf16_f32 v28, v34, v35
	v_cvt_pk_bf16_f32 v29, v36, v37
	v_cvt_pk_bf16_f32 v10, v22, v23
	v_cvt_pk_bf16_f32 v11, v24, v25
	v_cvt_pk_bf16_f32 v12, v18, v19
	v_cvt_pk_bf16_f32 v13, v20, v21
	v_lshl_add_u64 v[14:15], v[14:15], 0, v[124:125]
	v_cvt_pk_bf16_f32 v6, v6, v7
	v_cvt_pk_bf16_f32 v7, v8, v9
	v_cvt_pk_bf16_f32 v8, v2, v3
	v_cvt_pk_bf16_f32 v9, v4, v5
	s_andn2_b64 vcc, exec, s[80:81]
	s_mov_b64 s[4:5], -1
	global_store_dwordx4 v[122:123], v[126:129], off
	global_store_dwordx4 v[110:111], v[106:109], off
	global_store_dwordx4 v[94:95], v[90:93], off
	global_store_dwordx4 v[78:79], v[74:77], off
	global_store_dwordx4 v[78:79], v[70:73], off offset:1024
	global_store_dwordx4 v[58:59], v[62:65], off
	global_store_dwordx4 v[46:47], v[42:45], off
	global_store_dwordx4 v[30:31], v[26:29], off
	global_store_dwordx4 v[14:15], v[10:13], off
	global_store_dwordx4 v[14:15], v[6:9], off offset:1024
	s_cbranch_vccnz .LBB0_506
	s_andn2_b64 vcc, exec, s[40:41]
	s_cbranch_vccnz .LBB0_505
	s_barrier
	s_branch .LBB0_505

; __device__ __forceinline__ float sigmoid_f(float x) { return __builtin_amdgcn_rcpf(1.0f + __builtin_amdgcn_exp2f(-1.4426950409f * x)); }
; __device__ __forceinline__ u32x4 pack8(f32x4 a, f32x4 b) { u32x4 w; w.x = cvt_pk_bf16(a[0], a[1]); w.y = cvt_pk_bf16(a[2], a[3]); w.z = cvt_pk_bf16(b[0], b[1]); w.w = cvt_pk_bf16(b[2], b[3]); return w; }
; __device__ __forceinline__ void unpack8(u32x4 g, f32x4& a, f32x4& b) { a = (f32x4){bf_lo(g.x), bf_hi(g.x), bf_lo(g.y), bf_hi(g.y)}; b = (f32x4){bf_lo(g.z), bf_hi(g.z), bf_lo(g.w), bf_hi(g.w)}; }
; #define GATE_LOAD(r, b) do { const int row_ = row0 + ((r) >> 2) * 128 + ((r) & 3) * 16; _Pragma("unroll") for (int bj = 0; bj < 2; ++bj) { const size_t off_ = (size_t)row_ * DM + col0 + bj * 128; \
;             hA[b][bj] = *(const u32x4*)(H1 + off_); pA[b][bj] = *(const u32x4*)(PLE + off_); } } while (0)
;     __device__ __forceinline__ void operator()(f32x4 (&acc)[2][2][4][2], const Unit& u, int wr, int wc, int fr, int fq) const {
;     ...
;         const int row0 = u.pm * 256 + wr * 64 + fr, col0 = u.pn * 256 + wc * 32 + 8 * fq;
;         u32x4 hA[2][2], pA[2][2];
;     ...
;         GATE_LOAD(0, 0);
; #pragma unroll
;         for (int r = 0; r < 8; ++r) {
;             const int ai = r >> 2, m = r & 3, b = r & 1;
;             if (r + 1 < 8) GATE_LOAD(r + 1, (r + 1) & 1);
;             const int row = row0 + ai * 128 + m * 16;
;             float ss = 0.f;
; #pragma unroll
;             for (int bj = 0; bj < 2; ++bj) {
;                 const size_t off = (size_t)row * DM + col0 + bj * 128;
;                 f32x4 p0, p1, o0, o1; unpack8(pA[b][bj], p0, p1); unpack8(hA[b][bj], o0, o1);
; #pragma unroll
;                 for (int j = 0; j < 4; ++j) { o0[j] += sigmoid_f(acc[ai][bj][m][0][j]) * p0[j]; o1[j] += sigmoid_f(acc[ai][bj][m][1][j]) * p1[j]; }
;                 *(u32x4*)(HB + off) = pack8(o0, o1);
; #pragma unroll
;                 for (int j = 0; j < 4; ++j) ss += o0[j] * o0[j] + o1[j] * o1[j];
;             }
;             ss += __shfl_xor(ss, 16); ss += __shfl_xor(ss, 32);
.LBB0_802:
	s_lshl_b32 s4, s94, 8
	v_mov_b32_e32 v122, v1
	v_mov_b32_e32 v130, v208
	s_add_i32 s4, s4, s18
	s_mul_i32 s98, s92, 0x1e00
	s_mul_i32 s99, s19, 62
	s_add_i32 s98, s98, s99
	s_movk_i32 s99, 0xf010
	v_lshlrev_b32_e32 v246, 8, v208
	v_lshlrev_b32_e32 v247, 4, v208
	v_sub_u32_e32 v246, v246, v247
	v_add_u32_e32 v246, s98, v246
	v_mad_i32_i24 v246, v1, s99, v246
	v_ashrrev_i32_e32 v247, 31, v246
	v_mul_f32_e32 v134, 0xbfb8aa3b, v134
	v_add_u32_e32 v182, s4, v122
	s_lshl_b32 s4, s92, 8
	s_or_b32 s4, s4, s19
	v_lshl_add_u32 v180, v130, 3, s4
	v_ashrrev_i32_e32 v183, 31, v182
	v_lshlrev_b64 v[122:123], 11, v[182:183]
	v_ashrrev_i32_e32 v181, 31, v180
	v_lshl_add_u64 v[122:123], v[122:123], 0, v[180:181]
	v_lshlrev_b64 v[122:123], 1, v[122:123]
	v_lshl_add_u64 v[124:125], s[66:67], 0, v[122:123]
	global_load_dwordx4 v[154:157], v[124:125], off
	v_lshl_add_u64 v[122:123], s[44:45], 0, v[122:123]
	v_lshl_add_u64 v[122:123], v[122:123], 0, v[246:247]
	global_load_dwordx4 v[158:161], v[122:123], off
	global_load_dwordx4 v[146:149], v[124:125], off offset:256
	global_load_dwordx4 v[150:153], v[122:123], off offset:1024
	v_and_b32_e32 v123, 64, v191
	v_xor_b32_e32 v122, 16, v191
	v_add_u32_e32 v123, 64, v123
	v_cmp_lt_i32_e32 vcc, v122, v123
	v_add_u32_e32 v184, 16, v182
	v_ashrrev_i32_e32 v185, 31, v184
	v_cndmask_b32_e32 v122, v191, v122, vcc
	v_lshlrev_b32_e32 v211, 2, v122
	v_xor_b32_e32 v122, 32, v191
	v_cmp_lt_i32_e32 vcc, v122, v123
	v_mul_f32_e32 v135, 0xbfb8aa3b, v135
	v_mul_f32_e32 v136, 0xbfb8aa3b, v136
	v_cndmask_b32_e32 v122, v191, v122, vcc
	v_lshlrev_b32_e32 v212, 2, v122
	v_lshlrev_b64 v[122:123], 11, v[184:185]
	v_lshl_add_u64 v[122:123], v[122:123], 0, v[180:181]
	v_lshlrev_b64 v[122:123], 1, v[122:123]
	v_cmp_eq_u32_e32 vcc, 0, v130
	v_lshl_add_u64 v[124:125], s[66:67], 0, v[122:123]
	v_lshl_add_u64 v[130:131], s[44:45], 0, v[122:123]
	v_lshl_add_u64 v[130:131], v[130:131], 0, v[246:247]
	global_load_dwordx4 v[138:141], v[124:125], off
	global_load_dwordx4 v[142:145], v[130:131], off
	s_nop 0
	global_load_dwordx4 v[122:125], v[124:125], off offset:256
	s_nop 0
	global_load_dwordx4 v[130:133], v[130:131], off offset:1024
	v_mul_f32_e32 v137, 0xbfb8aa3b, v137
	v_exp_f32_e32 v134, v134
	v_mul_f32_e32 v126, 0xbfb8aa3b, v126
	v_exp_f32_e32 v135, v135
	v_mul_f32_e32 v127, 0xbfb8aa3b, v127
	v_exp_f32_e32 v136, v136
	v_mul_f32_e32 v128, 0xbfb8aa3b, v128
	v_exp_f32_e32 v137, v137
	v_mul_f32_e32 v129, 0xbfb8aa3b, v129
	v_exp_f32_e32 v126, v126
	v_exp_f32_e32 v127, v127
	v_exp_f32_e32 v128, v128
	v_exp_f32_e32 v129, v129
	v_mul_f32_e32 v118, 0xbfb8aa3b, v118
	v_mul_f32_e32 v119, 0xbfb8aa3b, v119
	v_add_f32_e32 v134, 1.0, v134
	v_add_f32_e32 v135, 1.0, v135
	v_add_f32_e32 v136, 1.0, v136
	v_add_f32_e32 v137, 1.0, v137
	v_exp_f32_e32 v118, v118
	v_mul_f32_e32 v114, 0xbfb8aa3b, v114
	v_exp_f32_e32 v119, v119
	v_mul_f32_e32 v115, 0xbfb8aa3b, v115
	v_rcp_f32_e32 v134, v134
	v_add_f32_e32 v126, 1.0, v126
	v_rcp_f32_e32 v135, v135
	v_add_f32_e32 v127, 1.0, v127
	v_rcp_f32_e32 v136, v136
	v_add_f32_e32 v128, 1.0, v128
	v_rcp_f32_e32 v137, v137
	v_add_f32_e32 v129, 1.0, v129
	v_exp_f32_e32 v114, v114
	v_exp_f32_e32 v115, v115
	v_rcp_f32_e32 v126, v126
	v_rcp_f32_e32 v127, v127
	v_rcp_f32_e32 v128, v128
	v_rcp_f32_e32 v129, v129
	v_add_f32_e32 v118, 1.0, v118
	v_add_f32_e32 v119, 1.0, v119
	v_rcp_f32_e32 v118, v118
	v_add_f32_e32 v114, 1.0, v114
	v_rcp_f32_e32 v119, v119
	v_add_f32_e32 v115, 1.0, v115
	v_rcp_f32_e32 v114, v114
	v_rcp_f32_e32 v115, v115
	v_lshlrev_b64 v[186:187], 12, v[182:183]
	s_waitcnt vmcnt(0)
	v_lshlrev_b32_e32 v214, 16, v158
	v_and_b32_e32 v215, 0xffff0000, v158
	v_lshlrev_b32_e32 v216, 16, v154
	v_and_b32_e32 v217, 0xffff0000, v154
	v_lshlrev_b32_e32 v158, 16, v159
	v_and_b32_e32 v159, 0xffff0000, v159
	v_lshlrev_b32_e32 v154, 16, v155
	v_and_b32_e32 v155, 0xffff0000, v155
	v_pk_fma_f32 v[134:135], v[134:135], v[214:215], v[216:217]
	v_lshlrev_b32_e32 v214, 16, v160
	v_and_b32_e32 v215, 0xffff0000, v160
	v_lshlrev_b32_e32 v216, 16, v156
	v_and_b32_e32 v217, 0xffff0000, v156
	v_pk_fma_f32 v[136:137], v[136:137], v[158:159], v[154:155]
	v_lshlrev_b32_e32 v154, 16, v161
	v_and_b32_e32 v155, 0xffff0000, v161
	v_lshlrev_b32_e32 v156, 16, v157
	v_and_b32_e32 v157, 0xffff0000, v157
	v_pk_fma_f32 v[126:127], v[126:127], v[214:215], v[216:217]
	v_pk_fma_f32 v[128:129], v[128:129], v[154:155], v[156:157]
	v_cvt_pk_bf16_f32 v156, v126, v127
	v_cvt_pk_bf16_f32 v157, v128, v129
	v_pk_mul_f32 v[126:127], v[126:127], v[126:127]
	v_pk_mul_f32 v[128:129], v[128:129], v[128:129]
	v_cvt_pk_bf16_f32 v154, v134, v135
	v_cvt_pk_bf16_f32 v155, v136, v137
	v_pk_fma_f32 v[126:127], v[134:135], v[134:135], v[126:127]
	v_pk_fma_f32 v[128:129], v[136:137], v[136:137], v[128:129]
	v_lshlrev_b32_e32 v134, 16, v150
	v_and_b32_e32 v135, 0xffff0000, v150
	v_lshlrev_b32_e32 v136, 16, v146
	v_and_b32_e32 v137, 0xffff0000, v146
	v_pk_fma_f32 v[118:119], v[118:119], v[134:135], v[136:137]
	v_lshlrev_b32_e32 v134, 16, v152
	v_and_b32_e32 v135, 0xffff0000, v152
	v_lshlrev_b32_e32 v136, 16, v148
	v_and_b32_e32 v137, 0xffff0000, v148
	v_pk_fma_f32 v[134:135], v[114:115], v[134:135], v[136:137]
	v_mul_f32_e32 v115, 0xbfb8aa3b, v116
	v_exp_f32_e32 v115, v115
	v_mul_f32_e32 v114, 0xbfb8aa3b, v120
	v_exp_f32_e32 v114, v114
	v_lshlrev_b32_e32 v120, 16, v151
	v_add_f32_e32 v115, 1.0, v115
	v_rcp_f32_e32 v116, v115
	v_mul_f32_e32 v115, 0xbfb8aa3b, v121
	v_exp_f32_e32 v115, v115
	v_add_f32_e32 v114, 1.0, v114
	v_rcp_f32_e32 v114, v114
	v_and_b32_e32 v121, 0xffff0000, v151
	v_add_f32_e32 v115, 1.0, v115
	v_rcp_f32_e32 v115, v115
	v_lshlrev_b32_e32 v136, 16, v147
	v_and_b32_e32 v137, 0xffff0000, v147
	v_lshl_add_u64 v[158:159], s[0:1], 0, v[186:187]
	v_pk_fma_f32 v[120:121], v[114:115], v[120:121], v[136:137]
	v_mul_f32_e32 v114, 0xbfb8aa3b, v117
	v_exp_f32_e32 v114, v114
	v_and_b32_e32 v115, 0xffff0000, v153
	v_lshlrev_b32_e32 v136, 16, v149
	v_and_b32_e32 v137, 0xffff0000, v149
	v_add_f32_e32 v114, 1.0, v114
	v_rcp_f32_e32 v117, v114
	v_lshlrev_b32_e32 v114, 16, v153
	v_lshl_add_u64 v[158:159], v[180:181], 1, v[158:159]
	global_store_dwordx4 v[158:159], v[154:157], off
	v_pk_fma_f32 v[136:137], v[116:117], v[114:115], v[136:137]
	v_cvt_pk_bf16_f32 v114, v118, v119
	v_cvt_pk_bf16_f32 v115, v120, v121
	v_cvt_pk_bf16_f32 v116, v134, v135
	v_cvt_pk_bf16_f32 v117, v136, v137
	global_store_dwordx4 v[158:159], v[114:117], off offset:256
	s_nop 1
	v_pk_mul_f32 v[114:115], v[134:135], v[134:135]
	v_pk_mul_f32 v[116:117], v[136:137], v[136:137]
	v_pk_fma_f32 v[114:115], v[118:119], v[118:119], v[114:115]
	v_add_f32_e32 v118, v126, v127
	v_add_f32_e32 v118, v128, v118
	v_add_f32_e32 v118, v129, v118
	v_add_f32_e32 v114, v114, v118
	v_pk_fma_f32 v[116:117], v[120:121], v[120:121], v[116:117]
	v_add_f32_e32 v114, v115, v114
	v_add_f32_e32 v114, v116, v114
	v_add_f32_e32 v114, v117, v114
	ds_bpermute_b32 v115, v211, v114
	s_waitcnt lgkmcnt(0)
; __device__ __forceinline__ float sigmoid_f(float x) { return __builtin_amdgcn_rcpf(1.0f + __builtin_amdgcn_exp2f(-1.4426950409f * x)); }
; __device__ __forceinline__ u32x4 pack8(f32x4 a, f32x4 b) { u32x4 w; w.x = cvt_pk_bf16(a[0], a[1]); w.y = cvt_pk_bf16(a[2], a[3]); w.z = cvt_pk_bf16(b[0], b[1]); w.w = cvt_pk_bf16(b[2], b[3]); return w; }
; __device__ __forceinline__ void unpack8(u32x4 g, f32x4& a, f32x4& b) { a = (f32x4){bf_lo(g.x), bf_hi(g.x), bf_lo(g.y), bf_hi(g.y)}; b = (f32x4){bf_lo(g.z), bf_hi(g.z), bf_lo(g.w), bf_hi(g.w)}; }
; #define GATE_LOAD(r, b) do { const int row_ = row0 + ((r) >> 2) * 128 + ((r) & 3) * 16; _Pragma("unroll") for (int bj = 0; bj < 2; ++bj) { const size_t off_ = (size_t)row_ * DM + col0 + bj * 128; \
;             hA[b][bj] = *(const u32x4*)(H1 + off_); pA[b][bj] = *(const u32x4*)(PLE + off_); } } while (0)
;     __device__ __forceinline__ void operator()(f32x4 (&acc)[2][2][4][2], const Unit& u, int wr, int wc, int fr, int fq) const {
;     ...
;         GATE_LOAD(0, 0);
; #pragma unroll
;         for (int r = 0; r < 8; ++r) {
;             const int ai = r >> 2, m = r & 3, b = r & 1;
;             if (r + 1 < 8) GATE_LOAD(r + 1, (r + 1) & 1);
;             const int row = row0 + ai * 128 + m * 16;
;             float ss = 0.f;
; #pragma unroll
;             for (int bj = 0; bj < 2; ++bj) {
;                 const size_t off = (size_t)row * DM + col0 + bj * 128;
;                 f32x4 p0, p1, o0, o1; unpack8(pA[b][bj], p0, p1); unpack8(hA[b][bj], o0, o1);
; #pragma unroll
;                 for (int j = 0; j < 4; ++j) { o0[j] += sigmoid_f(acc[ai][bj][m][0][j]) * p0[j]; o1[j] += sigmoid_f(acc[ai][bj][m][1][j]) * p1[j]; }
;                 *(u32x4*)(HB + off) = pack8(o0, o1);
; #pragma unroll
;                 for (int j = 0; j < 4; ++j) ss += o0[j] * o0[j] + o1[j] * o1[j];
;             }
;             ss += __shfl_xor(ss, 16); ss += __shfl_xor(ss, 32);
;             if (fq == 0) atomicAdd(ssq + row, ss);
;             asm volatile("" ::: "memory");
	v_add_f32_e32 v114, v114, v115
	ds_bpermute_b32 v115, v212, v114
	s_and_saveexec_b64 s[4:5], vcc
	s_cbranch_execz .LBB0_804
	v_lshl_add_u64 v[116:117], v[182:183], 2, s[46:47]
	s_waitcnt lgkmcnt(0)
	v_add_f32_e32 v114, v114, v115
	global_atomic_add_f32 v[116:117], v114, off
.LBB0_804:
	s_or_b64 exec, exec, s[4:5]
	v_add_u32_e32 v146, 32, v182
	v_ashrrev_i32_e32 v147, 31, v146
	s_waitcnt lgkmcnt(0)
	v_lshlrev_b64 v[114:115], 11, v[146:147]
	v_lshl_add_u64 v[114:115], v[114:115], 0, v[180:181]
	v_lshlrev_b64 v[114:115], 1, v[114:115]
	v_lshl_add_u64 v[116:117], s[66:67], 0, v[114:115]
	v_lshl_add_u64 v[118:119], s[44:45], 0, v[114:115]
	v_lshl_add_u64 v[118:119], v[118:119], 0, v[246:247]
	global_load_dwordx4 v[126:129], v[116:117], off
	s_nop 0
	global_load_dwordx4 v[114:117], v[116:117], off offset:256
	s_nop 0
	global_load_dwordx4 v[134:137], v[118:119], off
	s_nop 0
	global_load_dwordx4 v[118:121], v[118:119], off offset:1024
	v_mul_f32_e32 v110, 0xbfb8aa3b, v110
	v_mul_f32_e32 v111, 0xbfb8aa3b, v111
	v_exp_f32_e32 v110, v110
	v_mul_f32_e32 v106, 0xbfb8aa3b, v106
	v_exp_f32_e32 v111, v111
	v_mul_f32_e32 v107, 0xbfb8aa3b, v107
	v_exp_f32_e32 v106, v106
	v_exp_f32_e32 v107, v107
	v_add_f32_e32 v110, 1.0, v110
	v_add_f32_e32 v111, 1.0, v111
	v_rcp_f32_e32 v110, v110
	v_add_f32_e32 v106, 1.0, v106
	v_rcp_f32_e32 v111, v111
	v_add_f32_e32 v107, 1.0, v107
	v_rcp_f32_e32 v106, v106
	v_rcp_f32_e32 v107, v107
	v_mul_f32_e32 v112, 0xbfb8aa3b, v112
	v_lshlrev_b32_e32 v150, 16, v142
	v_and_b32_e32 v151, 0xffff0000, v142
	v_lshlrev_b32_e32 v152, 16, v138
	v_and_b32_e32 v153, 0xffff0000, v138
	v_exp_f32_e32 v112, v112
	v_pk_fma_f32 v[110:111], v[110:111], v[150:151], v[152:153]
	v_lshlrev_b32_e32 v150, 16, v144
	v_and_b32_e32 v151, 0xffff0000, v144
	v_lshlrev_b32_e32 v152, 16, v140
	v_and_b32_e32 v153, 0xffff0000, v140
	v_pk_fma_f32 v[150:151], v[106:107], v[150:151], v[152:153]
	v_mul_f32_e32 v107, 0xbfb8aa3b, v108
	v_exp_f32_e32 v107, v107
	v_mul_f32_e32 v108, 0xbfb8aa3b, v113
	v_add_f32_e32 v106, 1.0, v112
	v_exp_f32_e32 v112, v108
	v_add_f32_e32 v107, 1.0, v107
	v_rcp_f32_e32 v108, v107
	v_mul_f32_e32 v109, 0xbfb8aa3b, v109
	v_add_f32_e32 v107, 1.0, v112
	v_rcp_f32_e32 v106, v106
	v_rcp_f32_e32 v107, v107
	v_exp_f32_e32 v109, v109
	v_mul_f32_e32 v102, 0xbfb8aa3b, v102
	v_mul_f32_e32 v103, 0xbfb8aa3b, v103
	v_lshlrev_b32_e32 v112, 16, v143
	v_and_b32_e32 v113, 0xffff0000, v143
	v_lshlrev_b32_e32 v138, 16, v139
	v_and_b32_e32 v139, 0xffff0000, v139
	v_exp_f32_e32 v102, v102
	v_mul_f32_e32 v98, 0xbfb8aa3b, v98
	v_exp_f32_e32 v103, v103
	v_mul_f32_e32 v99, 0xbfb8aa3b, v99
	v_pk_fma_f32 v[112:113], v[106:107], v[112:113], v[138:139]
	v_add_f32_e32 v106, 1.0, v109
	v_exp_f32_e32 v98, v98
	v_exp_f32_e32 v99, v99
	v_rcp_f32_e32 v109, v106
	v_add_f32_e32 v102, 1.0, v102
	v_add_f32_e32 v103, 1.0, v103
	v_lshlrev_b32_e32 v106, 16, v145
	v_and_b32_e32 v107, 0xffff0000, v145
	v_lshlrev_b32_e32 v138, 16, v141
	v_and_b32_e32 v139, 0xffff0000, v141
	v_rcp_f32_e32 v102, v102
	v_add_f32_e32 v98, 1.0, v98
	v_rcp_f32_e32 v103, v103
	v_add_f32_e32 v99, 1.0, v99
	v_pk_fma_f32 v[138:139], v[108:109], v[106:107], v[138:139]
	v_rcp_f32_e32 v98, v98
	v_rcp_f32_e32 v99, v99
	v_cvt_pk_bf16_f32 v109, v138, v139
	v_pk_mul_f32 v[140:141], v[150:151], v[150:151]
	v_pk_mul_f32 v[138:139], v[138:139], v[138:139]
	v_mul_f32_e32 v104, 0xbfb8aa3b, v104
	v_cvt_pk_bf16_f32 v106, v110, v111
	v_cvt_pk_bf16_f32 v107, v112, v113
	v_pk_fma_f32 v[110:111], v[110:111], v[110:111], v[140:141]
	v_pk_fma_f32 v[112:113], v[112:113], v[112:113], v[138:139]
	v_lshlrev_b32_e32 v138, 16, v130
	v_and_b32_e32 v139, 0xffff0000, v130
	v_lshlrev_b32_e32 v140, 16, v122
	v_and_b32_e32 v141, 0xffff0000, v122
	v_exp_f32_e32 v104, v104
	v_pk_fma_f32 v[102:103], v[102:103], v[138:139], v[140:141]
	v_lshlrev_b32_e32 v138, 16, v132
	v_and_b32_e32 v139, 0xffff0000, v132
	v_lshlrev_b32_e32 v140, 16, v124
	v_and_b32_e32 v141, 0xffff0000, v124
	v_pk_fma_f32 v[138:139], v[98:99], v[138:139], v[140:141]
	v_mul_f32_e32 v99, 0xbfb8aa3b, v100
	v_exp_f32_e32 v99, v99
	v_mul_f32_e32 v100, 0xbfb8aa3b, v105
	v_add_f32_e32 v98, 1.0, v104
	v_exp_f32_e32 v104, v100
	v_add_f32_e32 v99, 1.0, v99
	v_rcp_f32_e32 v100, v99
	v_mul_f32_e32 v101, 0xbfb8aa3b, v101
	v_add_f32_e32 v99, 1.0, v104
	v_rcp_f32_e32 v98, v98
	v_rcp_f32_e32 v99, v99
	v_exp_f32_e32 v101, v101
	v_lshlrev_b32_e32 v104, 16, v131
	v_and_b32_e32 v105, 0xffff0000, v131
	v_lshlrev_b32_e32 v122, 16, v123
	v_and_b32_e32 v123, 0xffff0000, v123
	v_pk_fma_f32 v[104:105], v[98:99], v[104:105], v[122:123]
	v_add_f32_e32 v98, 1.0, v101
	v_rcp_f32_e32 v101, v98
	v_lshlrev_b32_e32 v98, 16, v133
	v_and_b32_e32 v99, 0xffff0000, v133
	v_lshlrev_b32_e32 v122, 16, v125
	v_and_b32_e32 v123, 0xffff0000, v125
	v_add_f32_e32 v110, v110, v111
	v_pk_fma_f32 v[122:123], v[100:101], v[98:99], v[122:123]
	v_pk_mul_f32 v[98:99], v[138:139], v[138:139]
	v_add_f32_e32 v110, v112, v110
	v_pk_fma_f32 v[98:99], v[102:103], v[102:103], v[98:99]
	v_add_f32_e32 v110, v113, v110
	v_pk_mul_f32 v[100:101], v[122:123], v[122:123]
	v_add_f32_e32 v98, v98, v110
	v_pk_fma_f32 v[100:101], v[104:105], v[104:105], v[100:101]
	v_add_f32_e32 v98, v99, v98
	v_add_f32_e32 v98, v100, v98
	v_add_f32_e32 v101, v101, v98
	ds_bpermute_b32 v112, v211, v101
	v_lshlrev_b64 v[148:149], 12, v[184:185]
	v_lshl_add_u64 v[98:99], s[0:1], 0, v[148:149]
	v_lshl_add_u64 v[110:111], v[180:181], 1, v[98:99]
	v_cvt_pk_bf16_f32 v108, v150, v151
	s_waitcnt lgkmcnt(0)
	v_add_f32_e32 v98, v101, v112
	ds_bpermute_b32 v99, v212, v98
	v_cvt_pk_bf16_f32 v100, v102, v103
	v_cvt_pk_bf16_f32 v101, v104, v105
	v_cvt_pk_bf16_f32 v102, v138, v139
	v_cvt_pk_bf16_f32 v103, v122, v123
	global_store_dwordx4 v[110:111], v[106:109], off
	global_store_dwordx4 v[110:111], v[100:103], off offset:256
	s_and_saveexec_b64 s[4:5], vcc
	s_cbranch_execz .LBB0_806
	v_lshl_add_u64 v[100:101], v[184:185], 2, s[46:47]
	s_waitcnt lgkmcnt(0)
	v_add_f32_e32 v98, v98, v99
	global_atomic_add_f32 v[100:101], v98, off
; __device__ __forceinline__ float sigmoid_f(float x) { return __builtin_amdgcn_rcpf(1.0f + __builtin_amdgcn_exp2f(-1.4426950409f * x)); }
; __device__ __forceinline__ u32x4 pack8(f32x4 a, f32x4 b) { u32x4 w; w.x = cvt_pk_bf16(a[0], a[1]); w.y = cvt_pk_bf16(a[2], a[3]); w.z = cvt_pk_bf16(b[0], b[1]); w.w = cvt_pk_bf16(b[2], b[3]); return w; }
; __device__ __forceinline__ void unpack8(u32x4 g, f32x4& a, f32x4& b) { a = (f32x4){bf_lo(g.x), bf_hi(g.x), bf_lo(g.y), bf_hi(g.y)}; b = (f32x4){bf_lo(g.z), bf_hi(g.z), bf_lo(g.w), bf_hi(g.w)}; }
; #define GATE_LOAD(r, b) do { const int row_ = row0 + ((r) >> 2) * 128 + ((r) & 3) * 16; _Pragma("unroll") for (int bj = 0; bj < 2; ++bj) { const size_t off_ = (size_t)row_ * DM + col0 + bj * 128; \
;             hA[b][bj] = *(const u32x4*)(H1 + off_); pA[b][bj] = *(const u32x4*)(PLE + off_); } } while (0)
;     __device__ __forceinline__ void operator()(f32x4 (&acc)[2][2][4][2], const Unit& u, int wr, int wc, int fr, int fq) const {
;     ...
;         GATE_LOAD(0, 0);
; #pragma unroll
;         for (int r = 0; r < 8; ++r) {
;             const int ai = r >> 2, m = r & 3, b = r & 1;
;             if (r + 1 < 8) GATE_LOAD(r + 1, (r + 1) & 1);
;             const int row = row0 + ai * 128 + m * 16;
;             float ss = 0.f;
; #pragma unroll
;             for (int bj = 0; bj < 2; ++bj) {
;                 const size_t off = (size_t)row * DM + col0 + bj * 128;
;                 f32x4 p0, p1, o0, o1; unpack8(pA[b][bj], p0, p1); unpack8(hA[b][bj], o0, o1);
; #pragma unroll
;                 for (int j = 0; j < 4; ++j) { o0[j] += sigmoid_f(acc[ai][bj][m][0][j]) * p0[j]; o1[j] += sigmoid_f(acc[ai][bj][m][1][j]) * p1[j]; }
;                 *(u32x4*)(HB + off) = pack8(o0, o1);
; #pragma unroll
;                 for (int j = 0; j < 4; ++j) ss += o0[j] * o0[j] + o1[j] * o1[j];
;             }
;             ss += __shfl_xor(ss, 16); ss += __shfl_xor(ss, 32);
;             if (fq == 0) atomicAdd(ssq + row, ss);
;             asm volatile("" ::: "memory");
.LBB0_806:
	s_or_b64 exec, exec, s[4:5]
	v_add_u32_e32 v122, 48, v182
	v_ashrrev_i32_e32 v123, 31, v122
	s_waitcnt lgkmcnt(0)
	v_lshlrev_b64 v[98:99], 11, v[122:123]
	v_lshl_add_u64 v[98:99], v[98:99], 0, v[180:181]
	v_lshlrev_b64 v[98:99], 1, v[98:99]
	v_lshl_add_u64 v[100:101], s[66:67], 0, v[98:99]
	v_lshl_add_u64 v[102:103], s[44:45], 0, v[98:99]
	v_lshl_add_u64 v[102:103], v[102:103], 0, v[246:247]
	global_load_dwordx4 v[106:109], v[100:101], off
	s_nop 0
	global_load_dwordx4 v[98:101], v[100:101], off offset:256
	s_nop 0
	global_load_dwordx4 v[110:113], v[102:103], off
	s_nop 0
	global_load_dwordx4 v[102:105], v[102:103], off offset:1024
	v_mul_f32_e32 v94, 0xbfb8aa3b, v94
	v_mul_f32_e32 v95, 0xbfb8aa3b, v95
	v_exp_f32_e32 v94, v94
	v_mul_f32_e32 v90, 0xbfb8aa3b, v90
	v_exp_f32_e32 v95, v95
	v_mul_f32_e32 v91, 0xbfb8aa3b, v91
	v_exp_f32_e32 v90, v90
	v_exp_f32_e32 v91, v91
	v_add_f32_e32 v94, 1.0, v94
	v_add_f32_e32 v95, 1.0, v95
	v_rcp_f32_e32 v94, v94
	v_add_f32_e32 v90, 1.0, v90
	v_rcp_f32_e32 v95, v95
	v_add_f32_e32 v91, 1.0, v91
	v_rcp_f32_e32 v90, v90
	v_rcp_f32_e32 v91, v91
	v_mul_f32_e32 v96, 0xbfb8aa3b, v96
	s_waitcnt vmcnt(7)
	v_lshlrev_b32_e32 v130, 16, v134
	v_and_b32_e32 v131, 0xffff0000, v134
	v_lshlrev_b32_e32 v132, 16, v126
	v_and_b32_e32 v133, 0xffff0000, v126
	v_exp_f32_e32 v96, v96
	v_pk_fma_f32 v[94:95], v[94:95], v[130:131], v[132:133]
	v_lshlrev_b32_e32 v130, 16, v136
	v_and_b32_e32 v131, 0xffff0000, v136
	v_lshlrev_b32_e32 v132, 16, v128
	v_and_b32_e32 v133, 0xffff0000, v128
	v_pk_fma_f32 v[130:131], v[90:91], v[130:131], v[132:133]
	v_mul_f32_e32 v91, 0xbfb8aa3b, v92
	v_exp_f32_e32 v91, v91
	v_mul_f32_e32 v92, 0xbfb8aa3b, v97
	v_add_f32_e32 v90, 1.0, v96
	v_exp_f32_e32 v96, v92
	v_add_f32_e32 v91, 1.0, v91
	v_rcp_f32_e32 v92, v91
	v_mul_f32_e32 v93, 0xbfb8aa3b, v93
	v_add_f32_e32 v91, 1.0, v96
	v_rcp_f32_e32 v90, v90
	v_rcp_f32_e32 v91, v91
	v_exp_f32_e32 v93, v93
	v_mul_f32_e32 v86, 0xbfb8aa3b, v86
	v_mul_f32_e32 v87, 0xbfb8aa3b, v87
	v_lshlrev_b32_e32 v96, 16, v135
	v_and_b32_e32 v97, 0xffff0000, v135
	v_lshlrev_b32_e32 v126, 16, v127
	v_and_b32_e32 v127, 0xffff0000, v127
	v_exp_f32_e32 v86, v86
	v_mul_f32_e32 v82, 0xbfb8aa3b, v82
	v_exp_f32_e32 v87, v87
	v_mul_f32_e32 v83, 0xbfb8aa3b, v83
	v_pk_fma_f32 v[96:97], v[90:91], v[96:97], v[126:127]
	v_add_f32_e32 v90, 1.0, v93
	v_exp_f32_e32 v82, v82
	v_exp_f32_e32 v83, v83
	v_rcp_f32_e32 v93, v90
	v_add_f32_e32 v86, 1.0, v86
	v_add_f32_e32 v87, 1.0, v87
	v_lshlrev_b32_e32 v90, 16, v137
	v_and_b32_e32 v91, 0xffff0000, v137
	v_lshlrev_b32_e32 v126, 16, v129
	v_and_b32_e32 v127, 0xffff0000, v129
	v_rcp_f32_e32 v86, v86
	v_add_f32_e32 v82, 1.0, v82
	v_rcp_f32_e32 v87, v87
	v_add_f32_e32 v83, 1.0, v83
	v_pk_fma_f32 v[126:127], v[92:93], v[90:91], v[126:127]
	v_rcp_f32_e32 v82, v82
	v_rcp_f32_e32 v83, v83
	v_cvt_pk_bf16_f32 v93, v126, v127
	v_pk_mul_f32 v[128:129], v[130:131], v[130:131]
	v_pk_mul_f32 v[126:127], v[126:127], v[126:127]
	v_mul_f32_e32 v88, 0xbfb8aa3b, v88
	v_cvt_pk_bf16_f32 v90, v94, v95
	v_cvt_pk_bf16_f32 v91, v96, v97
	v_pk_fma_f32 v[94:95], v[94:95], v[94:95], v[128:129]
	v_pk_fma_f32 v[96:97], v[96:97], v[96:97], v[126:127]
	s_waitcnt vmcnt(6)
	v_lshlrev_b32_e32 v126, 16, v118
	v_and_b32_e32 v127, 0xffff0000, v118
	v_lshlrev_b32_e32 v128, 16, v114
	v_and_b32_e32 v129, 0xffff0000, v114
	v_exp_f32_e32 v88, v88
	v_pk_fma_f32 v[86:87], v[86:87], v[126:127], v[128:129]
	v_lshlrev_b32_e32 v126, 16, v120
	v_and_b32_e32 v127, 0xffff0000, v120
	v_lshlrev_b32_e32 v128, 16, v116
	v_and_b32_e32 v129, 0xffff0000, v116
	v_pk_fma_f32 v[126:127], v[82:83], v[126:127], v[128:129]
	v_mul_f32_e32 v83, 0xbfb8aa3b, v84
	v_exp_f32_e32 v83, v83
	v_mul_f32_e32 v84, 0xbfb8aa3b, v89
	v_add_f32_e32 v82, 1.0, v88
	v_exp_f32_e32 v88, v84
	v_add_f32_e32 v83, 1.0, v83
	v_rcp_f32_e32 v84, v83
	v_mul_f32_e32 v85, 0xbfb8aa3b, v85
	v_add_f32_e32 v83, 1.0, v88
	v_rcp_f32_e32 v82, v82
	v_rcp_f32_e32 v83, v83
	v_exp_f32_e32 v85, v85
	v_lshlrev_b32_e32 v88, 16, v119
	v_and_b32_e32 v89, 0xffff0000, v119
	v_lshlrev_b32_e32 v114, 16, v115
	v_and_b32_e32 v115, 0xffff0000, v115
	v_pk_fma_f32 v[88:89], v[82:83], v[88:89], v[114:115]
	v_add_f32_e32 v82, 1.0, v85
	v_rcp_f32_e32 v85, v82
	v_lshlrev_b32_e32 v82, 16, v121
	v_and_b32_e32 v83, 0xffff0000, v121
	v_lshlrev_b32_e32 v114, 16, v117
	v_and_b32_e32 v115, 0xffff0000, v117
	v_add_f32_e32 v94, v94, v95
	v_pk_fma_f32 v[114:115], v[84:85], v[82:83], v[114:115]
	v_pk_mul_f32 v[82:83], v[126:127], v[126:127]
	v_add_f32_e32 v94, v96, v94
	v_pk_fma_f32 v[82:83], v[86:87], v[86:87], v[82:83]
	v_add_f32_e32 v94, v97, v94
	v_pk_mul_f32 v[84:85], v[114:115], v[114:115]
	v_add_f32_e32 v82, v82, v94
	v_pk_fma_f32 v[84:85], v[88:89], v[88:89], v[84:85]
	v_add_f32_e32 v82, v83, v82
	v_add_f32_e32 v82, v84, v82
	v_add_f32_e32 v85, v85, v82
	ds_bpermute_b32 v96, v211, v85
	v_lshlrev_b64 v[124:125], 12, v[146:147]
	v_lshl_add_u64 v[82:83], s[0:1], 0, v[124:125]
	v_lshl_add_u64 v[94:95], v[180:181], 1, v[82:83]
	v_cvt_pk_bf16_f32 v92, v130, v131
	s_waitcnt lgkmcnt(0)
	v_add_f32_e32 v82, v85, v96
	ds_bpermute_b32 v83, v212, v82
	v_cvt_pk_bf16_f32 v84, v86, v87
	v_cvt_pk_bf16_f32 v85, v88, v89
	v_cvt_pk_bf16_f32 v86, v126, v127
	v_cvt_pk_bf16_f32 v87, v114, v115
	global_store_dwordx4 v[94:95], v[90:93], off
	global_store_dwordx4 v[94:95], v[84:87], off offset:256
	s_and_saveexec_b64 s[4:5], vcc
	s_cbranch_execz .LBB0_808
	v_lshl_add_u64 v[84:85], v[146:147], 2, s[46:47]
	s_waitcnt lgkmcnt(0)
	v_add_f32_e32 v82, v82, v83
	global_atomic_add_f32 v[84:85], v82, off
; __device__ __forceinline__ float sigmoid_f(float x) { return __builtin_amdgcn_rcpf(1.0f + __builtin_amdgcn_exp2f(-1.4426950409f * x)); }
; __device__ __forceinline__ u32x4 pack8(f32x4 a, f32x4 b) { u32x4 w; w.x = cvt_pk_bf16(a[0], a[1]); w.y = cvt_pk_bf16(a[2], a[3]); w.z = cvt_pk_bf16(b[0], b[1]); w.w = cvt_pk_bf16(b[2], b[3]); return w; }
; __device__ __forceinline__ void unpack8(u32x4 g, f32x4& a, f32x4& b) { a = (f32x4){bf_lo(g.x), bf_hi(g.x), bf_lo(g.y), bf_hi(g.y)}; b = (f32x4){bf_lo(g.z), bf_hi(g.z), bf_lo(g.w), bf_hi(g.w)}; }
; #define GATE_LOAD(r, b) do { const int row_ = row0 + ((r) >> 2) * 128 + ((r) & 3) * 16; _Pragma("unroll") for (int bj = 0; bj < 2; ++bj) { const size_t off_ = (size_t)row_ * DM + col0 + bj * 128; \
;             hA[b][bj] = *(const u32x4*)(H1 + off_); pA[b][bj] = *(const u32x4*)(PLE + off_); } } while (0)
;     __device__ __forceinline__ void operator()(f32x4 (&acc)[2][2][4][2], const Unit& u, int wr, int wc, int fr, int fq) const {
;     ...
;         GATE_LOAD(0, 0);
; #pragma unroll
;         for (int r = 0; r < 8; ++r) {
;             const int ai = r >> 2, m = r & 3, b = r & 1;
;             if (r + 1 < 8) GATE_LOAD(r + 1, (r + 1) & 1);
;             const int row = row0 + ai * 128 + m * 16;
;             float ss = 0.f;
; #pragma unroll
;             for (int bj = 0; bj < 2; ++bj) {
;                 const size_t off = (size_t)row * DM + col0 + bj * 128;
;                 f32x4 p0, p1, o0, o1; unpack8(pA[b][bj], p0, p1); unpack8(hA[b][bj], o0, o1);
; #pragma unroll
;                 for (int j = 0; j < 4; ++j) { o0[j] += sigmoid_f(acc[ai][bj][m][0][j]) * p0[j]; o1[j] += sigmoid_f(acc[ai][bj][m][1][j]) * p1[j]; }
;                 *(u32x4*)(HB + off) = pack8(o0, o1);
; #pragma unroll
;                 for (int j = 0; j < 4; ++j) ss += o0[j] * o0[j] + o1[j] * o1[j];
;             }
;             ss += __shfl_xor(ss, 16); ss += __shfl_xor(ss, 32);
;             if (fq == 0) atomicAdd(ssq + row, ss);
;             asm volatile("" ::: "memory");
.LBB0_808:
	s_or_b64 exec, exec, s[4:5]
	v_add_u32_e32 v114, 0x80, v182
	v_ashrrev_i32_e32 v115, 31, v114
	s_waitcnt lgkmcnt(0)
	v_lshlrev_b64 v[82:83], 11, v[114:115]
	v_lshl_add_u64 v[82:83], v[82:83], 0, v[180:181]
	v_lshlrev_b64 v[82:83], 1, v[82:83]
	v_lshl_add_u64 v[84:85], s[66:67], 0, v[82:83]
	v_lshl_add_u64 v[86:87], s[44:45], 0, v[82:83]
	v_lshl_add_u64 v[86:87], v[86:87], 0, v[246:247]
	global_load_dwordx4 v[90:93], v[84:85], off
	s_nop 0
	global_load_dwordx4 v[82:85], v[84:85], off offset:256
	s_nop 0
	global_load_dwordx4 v[94:97], v[86:87], off
	s_nop 0
	global_load_dwordx4 v[86:89], v[86:87], off offset:1024
	v_mul_f32_e32 v78, 0xbfb8aa3b, v78
	v_mul_f32_e32 v79, 0xbfb8aa3b, v79
	v_exp_f32_e32 v78, v78
	v_mul_f32_e32 v74, 0xbfb8aa3b, v74
	v_exp_f32_e32 v79, v79
	v_mul_f32_e32 v75, 0xbfb8aa3b, v75
	v_exp_f32_e32 v74, v74
	v_exp_f32_e32 v75, v75
	v_add_f32_e32 v78, 1.0, v78
	v_add_f32_e32 v79, 1.0, v79
	v_rcp_f32_e32 v78, v78
	v_add_f32_e32 v74, 1.0, v74
	v_rcp_f32_e32 v79, v79
	v_add_f32_e32 v75, 1.0, v75
	v_rcp_f32_e32 v74, v74
	v_rcp_f32_e32 v75, v75
	v_mul_f32_e32 v80, 0xbfb8aa3b, v80
	s_waitcnt vmcnt(7)
	v_lshlrev_b32_e32 v118, 16, v110
	v_and_b32_e32 v119, 0xffff0000, v110
	v_lshlrev_b32_e32 v120, 16, v106
	v_and_b32_e32 v121, 0xffff0000, v106
	v_exp_f32_e32 v80, v80
	v_pk_fma_f32 v[78:79], v[78:79], v[118:119], v[120:121]
	v_lshlrev_b32_e32 v118, 16, v112
	v_and_b32_e32 v119, 0xffff0000, v112
	v_lshlrev_b32_e32 v120, 16, v108
	v_and_b32_e32 v121, 0xffff0000, v108
	v_pk_fma_f32 v[118:119], v[74:75], v[118:119], v[120:121]
	v_mul_f32_e32 v75, 0xbfb8aa3b, v76
	v_exp_f32_e32 v75, v75
	v_mul_f32_e32 v76, 0xbfb8aa3b, v81
	v_add_f32_e32 v74, 1.0, v80
	v_exp_f32_e32 v80, v76
	v_add_f32_e32 v75, 1.0, v75
	v_rcp_f32_e32 v76, v75
	v_mul_f32_e32 v77, 0xbfb8aa3b, v77
	v_add_f32_e32 v75, 1.0, v80
	v_rcp_f32_e32 v74, v74
	v_rcp_f32_e32 v75, v75
	v_exp_f32_e32 v77, v77
	v_mul_f32_e32 v70, 0xbfb8aa3b, v70
	v_mul_f32_e32 v71, 0xbfb8aa3b, v71
	v_lshlrev_b32_e32 v80, 16, v111
	v_and_b32_e32 v81, 0xffff0000, v111
	v_lshlrev_b32_e32 v106, 16, v107
	v_and_b32_e32 v107, 0xffff0000, v107
	v_exp_f32_e32 v70, v70
	v_mul_f32_e32 v66, 0xbfb8aa3b, v66
	v_exp_f32_e32 v71, v71
	v_mul_f32_e32 v67, 0xbfb8aa3b, v67
	v_pk_fma_f32 v[80:81], v[74:75], v[80:81], v[106:107]
	v_add_f32_e32 v74, 1.0, v77
	v_exp_f32_e32 v66, v66
	v_exp_f32_e32 v67, v67
	v_rcp_f32_e32 v77, v74
	v_add_f32_e32 v70, 1.0, v70
	v_add_f32_e32 v71, 1.0, v71
	v_lshlrev_b32_e32 v74, 16, v113
	v_and_b32_e32 v75, 0xffff0000, v113
	v_lshlrev_b32_e32 v106, 16, v109
	v_and_b32_e32 v107, 0xffff0000, v109
	v_rcp_f32_e32 v70, v70
	v_add_f32_e32 v66, 1.0, v66
	v_rcp_f32_e32 v71, v71
	v_add_f32_e32 v67, 1.0, v67
	v_pk_fma_f32 v[106:107], v[76:77], v[74:75], v[106:107]
	v_rcp_f32_e32 v66, v66
	v_rcp_f32_e32 v67, v67
	v_cvt_pk_bf16_f32 v77, v106, v107
	v_pk_mul_f32 v[108:109], v[118:119], v[118:119]
	v_pk_mul_f32 v[106:107], v[106:107], v[106:107]
	v_mul_f32_e32 v72, 0xbfb8aa3b, v72
	v_cvt_pk_bf16_f32 v74, v78, v79
	v_cvt_pk_bf16_f32 v75, v80, v81
	v_pk_fma_f32 v[78:79], v[78:79], v[78:79], v[108:109]
	v_pk_fma_f32 v[80:81], v[80:81], v[80:81], v[106:107]
	s_waitcnt vmcnt(6)
	v_lshlrev_b32_e32 v106, 16, v102
	v_and_b32_e32 v107, 0xffff0000, v102
	v_lshlrev_b32_e32 v108, 16, v98
	v_and_b32_e32 v109, 0xffff0000, v98
	v_exp_f32_e32 v72, v72
	v_pk_fma_f32 v[70:71], v[70:71], v[106:107], v[108:109]
	v_lshlrev_b32_e32 v106, 16, v104
	v_and_b32_e32 v107, 0xffff0000, v104
	v_lshlrev_b32_e32 v108, 16, v100
	v_and_b32_e32 v109, 0xffff0000, v100
	v_pk_fma_f32 v[106:107], v[66:67], v[106:107], v[108:109]
	v_mul_f32_e32 v67, 0xbfb8aa3b, v68
	v_exp_f32_e32 v67, v67
	v_mul_f32_e32 v68, 0xbfb8aa3b, v73
	v_add_f32_e32 v66, 1.0, v72
	v_exp_f32_e32 v72, v68
	v_add_f32_e32 v67, 1.0, v67
	v_rcp_f32_e32 v68, v67
	v_mul_f32_e32 v69, 0xbfb8aa3b, v69
	v_add_f32_e32 v67, 1.0, v72
	v_rcp_f32_e32 v66, v66
	v_rcp_f32_e32 v67, v67
	v_exp_f32_e32 v69, v69
	v_lshlrev_b32_e32 v72, 16, v103
	v_and_b32_e32 v73, 0xffff0000, v103
	v_lshlrev_b32_e32 v98, 16, v99
	v_and_b32_e32 v99, 0xffff0000, v99
	v_pk_fma_f32 v[72:73], v[66:67], v[72:73], v[98:99]
	v_add_f32_e32 v66, 1.0, v69
	v_rcp_f32_e32 v69, v66
	v_lshlrev_b32_e32 v66, 16, v105
	v_and_b32_e32 v67, 0xffff0000, v105
	v_lshlrev_b32_e32 v98, 16, v101
	v_and_b32_e32 v99, 0xffff0000, v101
	v_add_f32_e32 v78, v78, v79
	v_pk_fma_f32 v[98:99], v[68:69], v[66:67], v[98:99]
	v_pk_mul_f32 v[66:67], v[106:107], v[106:107]
	v_add_f32_e32 v78, v80, v78
	v_pk_fma_f32 v[66:67], v[70:71], v[70:71], v[66:67]
	v_add_f32_e32 v78, v81, v78
	v_pk_mul_f32 v[68:69], v[98:99], v[98:99]
	v_add_f32_e32 v66, v66, v78
	v_pk_fma_f32 v[68:69], v[72:73], v[72:73], v[68:69]
	v_add_f32_e32 v66, v67, v66
	v_add_f32_e32 v66, v68, v66
	v_add_f32_e32 v69, v69, v66
	ds_bpermute_b32 v80, v211, v69
	v_lshlrev_b64 v[116:117], 12, v[122:123]
	v_lshl_add_u64 v[66:67], s[0:1], 0, v[116:117]
	v_lshl_add_u64 v[78:79], v[180:181], 1, v[66:67]
	v_cvt_pk_bf16_f32 v76, v118, v119
	s_waitcnt lgkmcnt(0)
	v_add_f32_e32 v66, v69, v80
	ds_bpermute_b32 v67, v212, v66
	v_cvt_pk_bf16_f32 v68, v70, v71
	v_cvt_pk_bf16_f32 v69, v72, v73
	v_cvt_pk_bf16_f32 v70, v106, v107
	v_cvt_pk_bf16_f32 v71, v98, v99
	global_store_dwordx4 v[78:79], v[74:77], off
	global_store_dwordx4 v[78:79], v[68:71], off offset:256
	s_and_saveexec_b64 s[4:5], vcc
	s_cbranch_execz .LBB0_810
	v_lshl_add_u64 v[68:69], v[122:123], 2, s[46:47]
	s_waitcnt lgkmcnt(0)
	v_add_f32_e32 v66, v66, v67
	global_atomic_add_f32 v[68:69], v66, off
; __device__ __forceinline__ float sigmoid_f(float x) { return __builtin_amdgcn_rcpf(1.0f + __builtin_amdgcn_exp2f(-1.4426950409f * x)); }
; __device__ __forceinline__ u32x4 pack8(f32x4 a, f32x4 b) { u32x4 w; w.x = cvt_pk_bf16(a[0], a[1]); w.y = cvt_pk_bf16(a[2], a[3]); w.z = cvt_pk_bf16(b[0], b[1]); w.w = cvt_pk_bf16(b[2], b[3]); return w; }
; __device__ __forceinline__ void unpack8(u32x4 g, f32x4& a, f32x4& b) { a = (f32x4){bf_lo(g.x), bf_hi(g.x), bf_lo(g.y), bf_hi(g.y)}; b = (f32x4){bf_lo(g.z), bf_hi(g.z), bf_lo(g.w), bf_hi(g.w)}; }
; #define GATE_LOAD(r, b) do { const int row_ = row0 + ((r) >> 2) * 128 + ((r) & 3) * 16; _Pragma("unroll") for (int bj = 0; bj < 2; ++bj) { const size_t off_ = (size_t)row_ * DM + col0 + bj * 128; \
;             hA[b][bj] = *(const u32x4*)(H1 + off_); pA[b][bj] = *(const u32x4*)(PLE + off_); } } while (0)
;     __device__ __forceinline__ void operator()(f32x4 (&acc)[2][2][4][2], const Unit& u, int wr, int wc, int fr, int fq) const {
;     ...
;         GATE_LOAD(0, 0);
; #pragma unroll
;         for (int r = 0; r < 8; ++r) {
;             const int ai = r >> 2, m = r & 3, b = r & 1;
;             if (r + 1 < 8) GATE_LOAD(r + 1, (r + 1) & 1);
;             const int row = row0 + ai * 128 + m * 16;
;             float ss = 0.f;
; #pragma unroll
;             for (int bj = 0; bj < 2; ++bj) {
;                 const size_t off = (size_t)row * DM + col0 + bj * 128;
;                 f32x4 p0, p1, o0, o1; unpack8(pA[b][bj], p0, p1); unpack8(hA[b][bj], o0, o1);
; #pragma unroll
;                 for (int j = 0; j < 4; ++j) { o0[j] += sigmoid_f(acc[ai][bj][m][0][j]) * p0[j]; o1[j] += sigmoid_f(acc[ai][bj][m][1][j]) * p1[j]; }
;                 *(u32x4*)(HB + off) = pack8(o0, o1);
; #pragma unroll
;                 for (int j = 0; j < 4; ++j) ss += o0[j] * o0[j] + o1[j] * o1[j];
;             }
;             ss += __shfl_xor(ss, 16); ss += __shfl_xor(ss, 32);
;             if (fq == 0) atomicAdd(ssq + row, ss);
;             asm volatile("" ::: "memory");
.LBB0_810:
	s_or_b64 exec, exec, s[4:5]
	v_add_u32_e32 v98, 0x90, v182
	v_ashrrev_i32_e32 v99, 31, v98
	s_waitcnt lgkmcnt(0)
	v_lshlrev_b64 v[66:67], 11, v[98:99]
	v_lshl_add_u64 v[66:67], v[66:67], 0, v[180:181]
	v_lshlrev_b64 v[66:67], 1, v[66:67]
	v_lshl_add_u64 v[68:69], s[66:67], 0, v[66:67]
	v_lshl_add_u64 v[70:71], s[44:45], 0, v[66:67]
	v_lshl_add_u64 v[70:71], v[70:71], 0, v[246:247]
	global_load_dwordx4 v[74:77], v[68:69], off
	s_nop 0
	global_load_dwordx4 v[66:69], v[68:69], off offset:256
	s_nop 0
	global_load_dwordx4 v[78:81], v[70:71], off
	s_nop 0
	global_load_dwordx4 v[70:73], v[70:71], off offset:1024
	v_mul_f32_e32 v62, 0xbfb8aa3b, v62
	v_mul_f32_e32 v63, 0xbfb8aa3b, v63
	v_exp_f32_e32 v62, v62
	v_mul_f32_e32 v58, 0xbfb8aa3b, v58
	v_exp_f32_e32 v63, v63
	v_mul_f32_e32 v59, 0xbfb8aa3b, v59
	v_exp_f32_e32 v58, v58
	v_exp_f32_e32 v59, v59
	v_add_f32_e32 v62, 1.0, v62
	v_add_f32_e32 v63, 1.0, v63
	v_rcp_f32_e32 v62, v62
	v_add_f32_e32 v58, 1.0, v58
	v_rcp_f32_e32 v63, v63
	v_add_f32_e32 v59, 1.0, v59
	v_rcp_f32_e32 v58, v58
	v_rcp_f32_e32 v59, v59
	v_mul_f32_e32 v64, 0xbfb8aa3b, v64
	s_waitcnt vmcnt(7)
	v_lshlrev_b32_e32 v102, 16, v94
	v_and_b32_e32 v103, 0xffff0000, v94
	v_lshlrev_b32_e32 v104, 16, v90
	v_and_b32_e32 v105, 0xffff0000, v90
	v_exp_f32_e32 v64, v64
	v_pk_fma_f32 v[62:63], v[62:63], v[102:103], v[104:105]
	v_lshlrev_b32_e32 v102, 16, v96
	v_and_b32_e32 v103, 0xffff0000, v96
	v_lshlrev_b32_e32 v104, 16, v92
	v_and_b32_e32 v105, 0xffff0000, v92
	v_pk_fma_f32 v[102:103], v[58:59], v[102:103], v[104:105]
	v_mul_f32_e32 v59, 0xbfb8aa3b, v60
	v_exp_f32_e32 v59, v59
	v_mul_f32_e32 v60, 0xbfb8aa3b, v65
	v_add_f32_e32 v58, 1.0, v64
	v_exp_f32_e32 v64, v60
	v_add_f32_e32 v59, 1.0, v59
	v_rcp_f32_e32 v60, v59
	v_mul_f32_e32 v61, 0xbfb8aa3b, v61
	v_add_f32_e32 v59, 1.0, v64
	v_rcp_f32_e32 v58, v58
	v_rcp_f32_e32 v59, v59
	v_exp_f32_e32 v61, v61
	v_mul_f32_e32 v54, 0xbfb8aa3b, v54
	v_mul_f32_e32 v55, 0xbfb8aa3b, v55
	v_lshlrev_b32_e32 v64, 16, v95
	v_and_b32_e32 v65, 0xffff0000, v95
	v_lshlrev_b32_e32 v90, 16, v91
	v_and_b32_e32 v91, 0xffff0000, v91
	v_exp_f32_e32 v54, v54
	v_mul_f32_e32 v50, 0xbfb8aa3b, v50
	v_exp_f32_e32 v55, v55
	v_mul_f32_e32 v51, 0xbfb8aa3b, v51
	v_pk_fma_f32 v[64:65], v[58:59], v[64:65], v[90:91]
	v_add_f32_e32 v58, 1.0, v61
	v_exp_f32_e32 v50, v50
	v_exp_f32_e32 v51, v51
	v_rcp_f32_e32 v61, v58
	v_add_f32_e32 v54, 1.0, v54
	v_add_f32_e32 v55, 1.0, v55
	v_lshlrev_b32_e32 v58, 16, v97
	v_and_b32_e32 v59, 0xffff0000, v97
	v_lshlrev_b32_e32 v90, 16, v93
	v_and_b32_e32 v91, 0xffff0000, v93
	v_rcp_f32_e32 v54, v54
	v_add_f32_e32 v50, 1.0, v50
	v_rcp_f32_e32 v55, v55
	v_add_f32_e32 v51, 1.0, v51
	v_pk_fma_f32 v[90:91], v[60:61], v[58:59], v[90:91]
	v_rcp_f32_e32 v50, v50
	v_rcp_f32_e32 v51, v51
	v_cvt_pk_bf16_f32 v61, v90, v91
	v_pk_mul_f32 v[92:93], v[102:103], v[102:103]
	v_pk_mul_f32 v[90:91], v[90:91], v[90:91]
	v_mul_f32_e32 v56, 0xbfb8aa3b, v56
	v_cvt_pk_bf16_f32 v58, v62, v63
	v_cvt_pk_bf16_f32 v59, v64, v65
	v_pk_fma_f32 v[62:63], v[62:63], v[62:63], v[92:93]
	v_pk_fma_f32 v[64:65], v[64:65], v[64:65], v[90:91]
	s_waitcnt vmcnt(6)
	v_lshlrev_b32_e32 v90, 16, v86
	v_and_b32_e32 v91, 0xffff0000, v86
	v_lshlrev_b32_e32 v92, 16, v82
	v_and_b32_e32 v93, 0xffff0000, v82
	v_exp_f32_e32 v56, v56
	v_pk_fma_f32 v[54:55], v[54:55], v[90:91], v[92:93]
	v_lshlrev_b32_e32 v90, 16, v88
	v_and_b32_e32 v91, 0xffff0000, v88
	v_lshlrev_b32_e32 v92, 16, v84
	v_and_b32_e32 v93, 0xffff0000, v84
	v_pk_fma_f32 v[90:91], v[50:51], v[90:91], v[92:93]
	v_mul_f32_e32 v51, 0xbfb8aa3b, v52
	v_exp_f32_e32 v51, v51
	v_mul_f32_e32 v52, 0xbfb8aa3b, v57
	v_add_f32_e32 v50, 1.0, v56
	v_exp_f32_e32 v56, v52
	v_add_f32_e32 v51, 1.0, v51
	v_rcp_f32_e32 v52, v51
	v_mul_f32_e32 v53, 0xbfb8aa3b, v53
	v_add_f32_e32 v51, 1.0, v56
	v_rcp_f32_e32 v50, v50
	v_rcp_f32_e32 v51, v51
	v_exp_f32_e32 v53, v53
	v_lshlrev_b32_e32 v56, 16, v87
	v_and_b32_e32 v57, 0xffff0000, v87
	v_lshlrev_b32_e32 v82, 16, v83
	v_and_b32_e32 v83, 0xffff0000, v83
	v_pk_fma_f32 v[56:57], v[50:51], v[56:57], v[82:83]
	v_add_f32_e32 v50, 1.0, v53
	v_rcp_f32_e32 v53, v50
	v_lshlrev_b32_e32 v50, 16, v89
	v_and_b32_e32 v51, 0xffff0000, v89
	v_lshlrev_b32_e32 v82, 16, v85
	v_and_b32_e32 v83, 0xffff0000, v85
	v_add_f32_e32 v62, v62, v63
	v_pk_fma_f32 v[82:83], v[52:53], v[50:51], v[82:83]
	v_pk_mul_f32 v[50:51], v[90:91], v[90:91]
	v_add_f32_e32 v62, v64, v62
	v_pk_fma_f32 v[50:51], v[54:55], v[54:55], v[50:51]
	v_add_f32_e32 v62, v65, v62
	v_pk_mul_f32 v[52:53], v[82:83], v[82:83]
	v_add_f32_e32 v50, v50, v62
	v_pk_fma_f32 v[52:53], v[56:57], v[56:57], v[52:53]
	v_add_f32_e32 v50, v51, v50
	v_add_f32_e32 v50, v52, v50
	v_add_f32_e32 v53, v53, v50
	ds_bpermute_b32 v64, v211, v53
	v_lshlrev_b64 v[100:101], 12, v[114:115]
	v_lshl_add_u64 v[50:51], s[0:1], 0, v[100:101]
	v_lshl_add_u64 v[62:63], v[180:181], 1, v[50:51]
	v_cvt_pk_bf16_f32 v60, v102, v103
	s_waitcnt lgkmcnt(0)
	v_add_f32_e32 v50, v53, v64
	ds_bpermute_b32 v51, v212, v50
	v_cvt_pk_bf16_f32 v52, v54, v55
	v_cvt_pk_bf16_f32 v53, v56, v57
	v_cvt_pk_bf16_f32 v54, v90, v91
	v_cvt_pk_bf16_f32 v55, v82, v83
	global_store_dwordx4 v[62:63], v[58:61], off
	global_store_dwordx4 v[62:63], v[52:55], off offset:256
	s_and_saveexec_b64 s[4:5], vcc
	s_cbranch_execz .LBB0_812
	v_lshl_add_u64 v[52:53], v[114:115], 2, s[46:47]
	s_waitcnt lgkmcnt(0)
	v_add_f32_e32 v50, v50, v51
	global_atomic_add_f32 v[52:53], v50, off
; __device__ __forceinline__ float sigmoid_f(float x) { return __builtin_amdgcn_rcpf(1.0f + __builtin_amdgcn_exp2f(-1.4426950409f * x)); }
; __device__ __forceinline__ u32x4 pack8(f32x4 a, f32x4 b) { u32x4 w; w.x = cvt_pk_bf16(a[0], a[1]); w.y = cvt_pk_bf16(a[2], a[3]); w.z = cvt_pk_bf16(b[0], b[1]); w.w = cvt_pk_bf16(b[2], b[3]); return w; }
; __device__ __forceinline__ void unpack8(u32x4 g, f32x4& a, f32x4& b) { a = (f32x4){bf_lo(g.x), bf_hi(g.x), bf_lo(g.y), bf_hi(g.y)}; b = (f32x4){bf_lo(g.z), bf_hi(g.z), bf_lo(g.w), bf_hi(g.w)}; }
; #define GATE_LOAD(r, b) do { const int row_ = row0 + ((r) >> 2) * 128 + ((r) & 3) * 16; _Pragma("unroll") for (int bj = 0; bj < 2; ++bj) { const size_t off_ = (size_t)row_ * DM + col0 + bj * 128; \
;             hA[b][bj] = *(const u32x4*)(H1 + off_); pA[b][bj] = *(const u32x4*)(PLE + off_); } } while (0)
;     __device__ __forceinline__ void operator()(f32x4 (&acc)[2][2][4][2], const Unit& u, int wr, int wc, int fr, int fq) const {
;     ...
;         GATE_LOAD(0, 0);
; #pragma unroll
;         for (int r = 0; r < 8; ++r) {
;             const int ai = r >> 2, m = r & 3, b = r & 1;
;             if (r + 1 < 8) GATE_LOAD(r + 1, (r + 1) & 1);
;             const int row = row0 + ai * 128 + m * 16;
;             float ss = 0.f;
; #pragma unroll
;             for (int bj = 0; bj < 2; ++bj) {
;                 const size_t off = (size_t)row * DM + col0 + bj * 128;
;                 f32x4 p0, p1, o0, o1; unpack8(pA[b][bj], p0, p1); unpack8(hA[b][bj], o0, o1);
; #pragma unroll
;                 for (int j = 0; j < 4; ++j) { o0[j] += sigmoid_f(acc[ai][bj][m][0][j]) * p0[j]; o1[j] += sigmoid_f(acc[ai][bj][m][1][j]) * p1[j]; }
;                 *(u32x4*)(HB + off) = pack8(o0, o1);
; #pragma unroll
;                 for (int j = 0; j < 4; ++j) ss += o0[j] * o0[j] + o1[j] * o1[j];
;             }
;             ss += __shfl_xor(ss, 16); ss += __shfl_xor(ss, 32);
;             if (fq == 0) atomicAdd(ssq + row, ss);
;             asm volatile("" ::: "memory");
.LBB0_812:
	s_or_b64 exec, exec, s[4:5]
	v_add_u32_e32 v82, 0xa0, v182
	v_ashrrev_i32_e32 v83, 31, v82
	s_waitcnt lgkmcnt(0)
	v_lshlrev_b64 v[50:51], 11, v[82:83]
	v_lshl_add_u64 v[50:51], v[50:51], 0, v[180:181]
	v_lshlrev_b64 v[50:51], 1, v[50:51]
	v_lshl_add_u64 v[52:53], s[66:67], 0, v[50:51]
	v_lshl_add_u64 v[54:55], s[44:45], 0, v[50:51]
	v_lshl_add_u64 v[54:55], v[54:55], 0, v[246:247]
	global_load_dwordx4 v[58:61], v[52:53], off
	s_nop 0
	global_load_dwordx4 v[50:53], v[52:53], off offset:256
	s_nop 0
	global_load_dwordx4 v[62:65], v[54:55], off
	s_nop 0
	global_load_dwordx4 v[54:57], v[54:55], off offset:1024
	v_mul_f32_e32 v46, 0xbfb8aa3b, v46
	v_mul_f32_e32 v47, 0xbfb8aa3b, v47
	v_exp_f32_e32 v46, v46
	v_mul_f32_e32 v42, 0xbfb8aa3b, v42
	v_exp_f32_e32 v47, v47
	v_mul_f32_e32 v43, 0xbfb8aa3b, v43
	v_exp_f32_e32 v42, v42
	v_exp_f32_e32 v43, v43
	v_add_f32_e32 v46, 1.0, v46
	v_add_f32_e32 v47, 1.0, v47
	v_rcp_f32_e32 v46, v46
	v_add_f32_e32 v42, 1.0, v42
	v_rcp_f32_e32 v47, v47
	v_add_f32_e32 v43, 1.0, v43
	v_rcp_f32_e32 v42, v42
	v_rcp_f32_e32 v43, v43
	v_mul_f32_e32 v48, 0xbfb8aa3b, v48
	s_waitcnt vmcnt(7)
	v_lshlrev_b32_e32 v86, 16, v78
	v_and_b32_e32 v87, 0xffff0000, v78
	v_lshlrev_b32_e32 v88, 16, v74
	v_and_b32_e32 v89, 0xffff0000, v74
	v_exp_f32_e32 v48, v48
	v_pk_fma_f32 v[46:47], v[46:47], v[86:87], v[88:89]
	v_lshlrev_b32_e32 v86, 16, v80
	v_and_b32_e32 v87, 0xffff0000, v80
	v_lshlrev_b32_e32 v88, 16, v76
	v_and_b32_e32 v89, 0xffff0000, v76
	v_pk_fma_f32 v[86:87], v[42:43], v[86:87], v[88:89]
	v_mul_f32_e32 v43, 0xbfb8aa3b, v44
	v_exp_f32_e32 v43, v43
	v_mul_f32_e32 v44, 0xbfb8aa3b, v49
	v_add_f32_e32 v42, 1.0, v48
	v_exp_f32_e32 v48, v44
	v_add_f32_e32 v43, 1.0, v43
	v_rcp_f32_e32 v44, v43
	v_mul_f32_e32 v45, 0xbfb8aa3b, v45
	v_add_f32_e32 v43, 1.0, v48
	v_rcp_f32_e32 v42, v42
	v_rcp_f32_e32 v43, v43
	v_exp_f32_e32 v45, v45
	v_mul_f32_e32 v38, 0xbfb8aa3b, v38
	v_mul_f32_e32 v39, 0xbfb8aa3b, v39
	v_lshlrev_b32_e32 v48, 16, v79
	v_and_b32_e32 v49, 0xffff0000, v79
	v_lshlrev_b32_e32 v74, 16, v75
	v_and_b32_e32 v75, 0xffff0000, v75
	v_exp_f32_e32 v38, v38
	v_mul_f32_e32 v34, 0xbfb8aa3b, v34
	v_exp_f32_e32 v39, v39
	v_mul_f32_e32 v35, 0xbfb8aa3b, v35
	v_pk_fma_f32 v[48:49], v[42:43], v[48:49], v[74:75]
	v_add_f32_e32 v42, 1.0, v45
	v_exp_f32_e32 v34, v34
	v_exp_f32_e32 v35, v35
	v_rcp_f32_e32 v45, v42
	v_add_f32_e32 v38, 1.0, v38
	v_add_f32_e32 v39, 1.0, v39
	v_lshlrev_b32_e32 v42, 16, v81
	v_and_b32_e32 v43, 0xffff0000, v81
	v_lshlrev_b32_e32 v74, 16, v77
	v_and_b32_e32 v75, 0xffff0000, v77
	v_rcp_f32_e32 v38, v38
	v_add_f32_e32 v34, 1.0, v34
	v_rcp_f32_e32 v39, v39
	v_add_f32_e32 v35, 1.0, v35
	v_pk_fma_f32 v[74:75], v[44:45], v[42:43], v[74:75]
	v_rcp_f32_e32 v34, v34
	v_rcp_f32_e32 v35, v35
	v_cvt_pk_bf16_f32 v45, v74, v75
	v_pk_mul_f32 v[76:77], v[86:87], v[86:87]
	v_pk_mul_f32 v[74:75], v[74:75], v[74:75]
	v_mul_f32_e32 v40, 0xbfb8aa3b, v40
	v_cvt_pk_bf16_f32 v42, v46, v47
	v_cvt_pk_bf16_f32 v43, v48, v49
	v_pk_fma_f32 v[46:47], v[46:47], v[46:47], v[76:77]
	v_pk_fma_f32 v[48:49], v[48:49], v[48:49], v[74:75]
	s_waitcnt vmcnt(6)
	v_lshlrev_b32_e32 v74, 16, v70
	v_and_b32_e32 v75, 0xffff0000, v70
	v_lshlrev_b32_e32 v76, 16, v66
	v_and_b32_e32 v77, 0xffff0000, v66
	v_exp_f32_e32 v40, v40
	v_pk_fma_f32 v[38:39], v[38:39], v[74:75], v[76:77]
	v_lshlrev_b32_e32 v74, 16, v72
	v_and_b32_e32 v75, 0xffff0000, v72
	v_lshlrev_b32_e32 v76, 16, v68
	v_and_b32_e32 v77, 0xffff0000, v68
	v_pk_fma_f32 v[74:75], v[34:35], v[74:75], v[76:77]
	v_mul_f32_e32 v35, 0xbfb8aa3b, v36
	v_exp_f32_e32 v35, v35
	v_mul_f32_e32 v36, 0xbfb8aa3b, v41
	v_add_f32_e32 v34, 1.0, v40
	v_exp_f32_e32 v40, v36
	v_add_f32_e32 v35, 1.0, v35
	v_rcp_f32_e32 v36, v35
	v_mul_f32_e32 v37, 0xbfb8aa3b, v37
	v_add_f32_e32 v35, 1.0, v40
	v_rcp_f32_e32 v34, v34
	v_rcp_f32_e32 v35, v35
	v_exp_f32_e32 v37, v37
	v_lshlrev_b32_e32 v40, 16, v71
	v_and_b32_e32 v41, 0xffff0000, v71
	v_lshlrev_b32_e32 v66, 16, v67
	v_and_b32_e32 v67, 0xffff0000, v67
	v_pk_fma_f32 v[40:41], v[34:35], v[40:41], v[66:67]
	v_add_f32_e32 v34, 1.0, v37
	v_rcp_f32_e32 v37, v34
	v_lshlrev_b32_e32 v34, 16, v73
	v_and_b32_e32 v35, 0xffff0000, v73
	v_lshlrev_b32_e32 v66, 16, v69
	v_and_b32_e32 v67, 0xffff0000, v69
	v_add_f32_e32 v46, v46, v47
	v_pk_fma_f32 v[66:67], v[36:37], v[34:35], v[66:67]
	v_pk_mul_f32 v[34:35], v[74:75], v[74:75]
	v_add_f32_e32 v46, v48, v46
	v_pk_fma_f32 v[34:35], v[38:39], v[38:39], v[34:35]
	v_add_f32_e32 v46, v49, v46
	v_pk_mul_f32 v[36:37], v[66:67], v[66:67]
	v_add_f32_e32 v34, v34, v46
	v_pk_fma_f32 v[36:37], v[40:41], v[40:41], v[36:37]
	v_add_f32_e32 v34, v35, v34
	v_add_f32_e32 v34, v36, v34
	v_add_f32_e32 v37, v37, v34
	ds_bpermute_b32 v48, v211, v37
	v_lshlrev_b64 v[84:85], 12, v[98:99]
	v_lshl_add_u64 v[34:35], s[0:1], 0, v[84:85]
	v_lshl_add_u64 v[46:47], v[180:181], 1, v[34:35]
	v_cvt_pk_bf16_f32 v44, v86, v87
	s_waitcnt lgkmcnt(0)
	v_add_f32_e32 v34, v37, v48
	ds_bpermute_b32 v35, v212, v34
	v_cvt_pk_bf16_f32 v36, v38, v39
	v_cvt_pk_bf16_f32 v37, v40, v41
	v_cvt_pk_bf16_f32 v38, v74, v75
	v_cvt_pk_bf16_f32 v39, v66, v67
	global_store_dwordx4 v[46:47], v[42:45], off
	global_store_dwordx4 v[46:47], v[36:39], off offset:256
	s_and_saveexec_b64 s[4:5], vcc
	s_cbranch_execz .LBB0_814
	v_lshl_add_u64 v[36:37], v[98:99], 2, s[46:47]
	s_waitcnt lgkmcnt(0)
	v_add_f32_e32 v34, v34, v35
	global_atomic_add_f32 v[36:37], v34, off
; __device__ __forceinline__ float sigmoid_f(float x) { return __builtin_amdgcn_rcpf(1.0f + __builtin_amdgcn_exp2f(-1.4426950409f * x)); }
; __device__ __forceinline__ u32x4 pack8(f32x4 a, f32x4 b) { u32x4 w; w.x = cvt_pk_bf16(a[0], a[1]); w.y = cvt_pk_bf16(a[2], a[3]); w.z = cvt_pk_bf16(b[0], b[1]); w.w = cvt_pk_bf16(b[2], b[3]); return w; }
; __device__ __forceinline__ void unpack8(u32x4 g, f32x4& a, f32x4& b) { a = (f32x4){bf_lo(g.x), bf_hi(g.x), bf_lo(g.y), bf_hi(g.y)}; b = (f32x4){bf_lo(g.z), bf_hi(g.z), bf_lo(g.w), bf_hi(g.w)}; }
; #define GATE_LOAD(r, b) do { const int row_ = row0 + ((r) >> 2) * 128 + ((r) & 3) * 16; _Pragma("unroll") for (int bj = 0; bj < 2; ++bj) { const size_t off_ = (size_t)row_ * DM + col0 + bj * 128; \
;             hA[b][bj] = *(const u32x4*)(H1 + off_); pA[b][bj] = *(const u32x4*)(PLE + off_); } } while (0)
;     __device__ __forceinline__ void operator()(f32x4 (&acc)[2][2][4][2], const Unit& u, int wr, int wc, int fr, int fq) const {
;     ...
;         GATE_LOAD(0, 0);
; #pragma unroll
;         for (int r = 0; r < 8; ++r) {
;             const int ai = r >> 2, m = r & 3, b = r & 1;
;             if (r + 1 < 8) GATE_LOAD(r + 1, (r + 1) & 1);
;             const int row = row0 + ai * 128 + m * 16;
;             float ss = 0.f;
; #pragma unroll
;             for (int bj = 0; bj < 2; ++bj) {
;                 const size_t off = (size_t)row * DM + col0 + bj * 128;
;                 f32x4 p0, p1, o0, o1; unpack8(pA[b][bj], p0, p1); unpack8(hA[b][bj], o0, o1);
; #pragma unroll
;                 for (int j = 0; j < 4; ++j) { o0[j] += sigmoid_f(acc[ai][bj][m][0][j]) * p0[j]; o1[j] += sigmoid_f(acc[ai][bj][m][1][j]) * p1[j]; }
;                 *(u32x4*)(HB + off) = pack8(o0, o1);
; #pragma unroll
;                 for (int j = 0; j < 4; ++j) ss += o0[j] * o0[j] + o1[j] * o1[j];
;             }
;             ss += __shfl_xor(ss, 16); ss += __shfl_xor(ss, 32);
;             if (fq == 0) atomicAdd(ssq + row, ss);
;             asm volatile("" ::: "memory");
.LBB0_814:
	s_or_b64 exec, exec, s[4:5]
	v_add_u32_e32 v66, 0xb0, v182
	v_ashrrev_i32_e32 v67, 31, v66
	s_waitcnt lgkmcnt(0)
	v_lshlrev_b64 v[34:35], 11, v[66:67]
	v_lshl_add_u64 v[34:35], v[34:35], 0, v[180:181]
	v_lshlrev_b64 v[34:35], 1, v[34:35]
	v_lshl_add_u64 v[36:37], s[66:67], 0, v[34:35]
	v_lshl_add_u64 v[38:39], s[44:45], 0, v[34:35]
	v_lshl_add_u64 v[38:39], v[38:39], 0, v[246:247]
	global_load_dwordx4 v[42:45], v[36:37], off
	s_nop 0
	global_load_dwordx4 v[34:37], v[36:37], off offset:256
	s_nop 0
	global_load_dwordx4 v[46:49], v[38:39], off
	s_nop 0
	global_load_dwordx4 v[38:41], v[38:39], off offset:1024
	v_mul_f32_e32 v30, 0xbfb8aa3b, v30
	v_mul_f32_e32 v31, 0xbfb8aa3b, v31
	v_exp_f32_e32 v30, v30
	v_mul_f32_e32 v26, 0xbfb8aa3b, v26
	v_exp_f32_e32 v31, v31
	v_mul_f32_e32 v27, 0xbfb8aa3b, v27
	v_exp_f32_e32 v26, v26
	v_exp_f32_e32 v27, v27
	v_add_f32_e32 v30, 1.0, v30
	v_add_f32_e32 v31, 1.0, v31
	v_rcp_f32_e32 v30, v30
	v_add_f32_e32 v26, 1.0, v26
	v_rcp_f32_e32 v31, v31
	v_add_f32_e32 v27, 1.0, v27
	v_rcp_f32_e32 v26, v26
	v_rcp_f32_e32 v27, v27
	v_mul_f32_e32 v32, 0xbfb8aa3b, v32
	s_waitcnt vmcnt(7)
	v_lshlrev_b32_e32 v70, 16, v62
	v_and_b32_e32 v71, 0xffff0000, v62
	v_lshlrev_b32_e32 v72, 16, v58
	v_and_b32_e32 v73, 0xffff0000, v58
	v_exp_f32_e32 v32, v32
	v_pk_fma_f32 v[30:31], v[30:31], v[70:71], v[72:73]
	v_lshlrev_b32_e32 v70, 16, v64
	v_and_b32_e32 v71, 0xffff0000, v64
	v_lshlrev_b32_e32 v72, 16, v60
	v_and_b32_e32 v73, 0xffff0000, v60
	v_pk_fma_f32 v[70:71], v[26:27], v[70:71], v[72:73]
	v_mul_f32_e32 v27, 0xbfb8aa3b, v28
	v_exp_f32_e32 v27, v27
	v_mul_f32_e32 v28, 0xbfb8aa3b, v33
	v_add_f32_e32 v26, 1.0, v32
	v_exp_f32_e32 v32, v28
	v_add_f32_e32 v27, 1.0, v27
	v_rcp_f32_e32 v28, v27
	v_mul_f32_e32 v29, 0xbfb8aa3b, v29
	v_add_f32_e32 v27, 1.0, v32
	v_rcp_f32_e32 v26, v26
	v_rcp_f32_e32 v27, v27
	v_exp_f32_e32 v29, v29
	v_mul_f32_e32 v22, 0xbfb8aa3b, v22
	v_mul_f32_e32 v23, 0xbfb8aa3b, v23
	v_lshlrev_b32_e32 v32, 16, v63
	v_and_b32_e32 v33, 0xffff0000, v63
	v_lshlrev_b32_e32 v58, 16, v59
	v_and_b32_e32 v59, 0xffff0000, v59
	v_exp_f32_e32 v22, v22
	v_mul_f32_e32 v18, 0xbfb8aa3b, v18
	v_exp_f32_e32 v23, v23
	v_mul_f32_e32 v19, 0xbfb8aa3b, v19
	v_pk_fma_f32 v[32:33], v[26:27], v[32:33], v[58:59]
	v_add_f32_e32 v26, 1.0, v29
	v_exp_f32_e32 v18, v18
	v_exp_f32_e32 v19, v19
	v_rcp_f32_e32 v29, v26
	v_add_f32_e32 v22, 1.0, v22
	v_add_f32_e32 v23, 1.0, v23
	v_lshlrev_b32_e32 v26, 16, v65
	v_and_b32_e32 v27, 0xffff0000, v65
	v_lshlrev_b32_e32 v58, 16, v61
	v_and_b32_e32 v59, 0xffff0000, v61
	v_rcp_f32_e32 v22, v22
	v_add_f32_e32 v18, 1.0, v18
	v_rcp_f32_e32 v23, v23
	v_add_f32_e32 v19, 1.0, v19
	v_pk_fma_f32 v[58:59], v[28:29], v[26:27], v[58:59]
	v_rcp_f32_e32 v18, v18
	v_rcp_f32_e32 v19, v19
	v_cvt_pk_bf16_f32 v29, v58, v59
	v_pk_mul_f32 v[60:61], v[70:71], v[70:71]
	v_pk_mul_f32 v[58:59], v[58:59], v[58:59]
	v_mul_f32_e32 v24, 0xbfb8aa3b, v24
	v_cvt_pk_bf16_f32 v26, v30, v31
	v_cvt_pk_bf16_f32 v27, v32, v33
	v_pk_fma_f32 v[30:31], v[30:31], v[30:31], v[60:61]
	v_pk_fma_f32 v[32:33], v[32:33], v[32:33], v[58:59]
	s_waitcnt vmcnt(6)
	v_lshlrev_b32_e32 v58, 16, v54
	v_and_b32_e32 v59, 0xffff0000, v54
	v_lshlrev_b32_e32 v60, 16, v50
	v_and_b32_e32 v61, 0xffff0000, v50
	v_exp_f32_e32 v24, v24
	v_pk_fma_f32 v[22:23], v[22:23], v[58:59], v[60:61]
	v_lshlrev_b32_e32 v58, 16, v56
	v_and_b32_e32 v59, 0xffff0000, v56
	v_lshlrev_b32_e32 v60, 16, v52
	v_and_b32_e32 v61, 0xffff0000, v52
	v_pk_fma_f32 v[58:59], v[18:19], v[58:59], v[60:61]
	v_mul_f32_e32 v19, 0xbfb8aa3b, v20
	v_exp_f32_e32 v19, v19
	v_mul_f32_e32 v20, 0xbfb8aa3b, v25
	v_add_f32_e32 v18, 1.0, v24
	v_exp_f32_e32 v24, v20
	v_add_f32_e32 v19, 1.0, v19
	v_rcp_f32_e32 v20, v19
	v_mul_f32_e32 v21, 0xbfb8aa3b, v21
	v_add_f32_e32 v19, 1.0, v24
	v_rcp_f32_e32 v18, v18
	v_rcp_f32_e32 v19, v19
	v_exp_f32_e32 v21, v21
	v_lshlrev_b32_e32 v24, 16, v55
	v_and_b32_e32 v25, 0xffff0000, v55
	v_lshlrev_b32_e32 v50, 16, v51
	v_and_b32_e32 v51, 0xffff0000, v51
	v_pk_fma_f32 v[24:25], v[18:19], v[24:25], v[50:51]
	v_add_f32_e32 v18, 1.0, v21
	v_rcp_f32_e32 v21, v18
	v_lshlrev_b32_e32 v18, 16, v57
	v_and_b32_e32 v19, 0xffff0000, v57
	v_lshlrev_b32_e32 v50, 16, v53
	v_and_b32_e32 v51, 0xffff0000, v53
	v_add_f32_e32 v30, v30, v31
	v_pk_fma_f32 v[50:51], v[20:21], v[18:19], v[50:51]
	v_pk_mul_f32 v[18:19], v[58:59], v[58:59]
	v_add_f32_e32 v30, v32, v30
	v_pk_fma_f32 v[18:19], v[22:23], v[22:23], v[18:19]
	v_add_f32_e32 v30, v33, v30
	v_pk_mul_f32 v[20:21], v[50:51], v[50:51]
	v_add_f32_e32 v18, v18, v30
	v_pk_fma_f32 v[20:21], v[24:25], v[24:25], v[20:21]
	v_add_f32_e32 v18, v19, v18
	v_add_f32_e32 v18, v20, v18
	v_add_f32_e32 v21, v21, v18
	ds_bpermute_b32 v32, v211, v21
	v_lshlrev_b64 v[68:69], 12, v[82:83]
	v_lshl_add_u64 v[18:19], s[0:1], 0, v[68:69]
	v_lshl_add_u64 v[30:31], v[180:181], 1, v[18:19]
	v_cvt_pk_bf16_f32 v28, v70, v71
	s_waitcnt lgkmcnt(0)
	v_add_f32_e32 v18, v21, v32
	ds_bpermute_b32 v19, v212, v18
	v_cvt_pk_bf16_f32 v20, v22, v23
	v_cvt_pk_bf16_f32 v21, v24, v25
	v_cvt_pk_bf16_f32 v22, v58, v59
	v_cvt_pk_bf16_f32 v23, v50, v51
	global_store_dwordx4 v[30:31], v[26:29], off
	global_store_dwordx4 v[30:31], v[20:23], off offset:256
	s_and_saveexec_b64 s[4:5], vcc
	s_cbranch_execz .LBB0_816
	v_lshl_add_u64 v[20:21], v[82:83], 2, s[46:47]
	s_waitcnt lgkmcnt(0)
	v_add_f32_e32 v18, v18, v19
	global_atomic_add_f32 v[20:21], v18, off
